# P58 + P60 combined (batched modulation loads in the input-conversion pass; RoPE table in static LDS with in-place LDS address and delayed staging write)
# baseline (speedup 1.0000x reference)
.LBB0_330:
	s_xor_b64 s[0:1], s[82:83], -1
	v_writelane_b32 v254, s0, 59
	s_mov_b64 s[22:23], s[88:89]
	s_mul_i32 s14, s16, 0x120000
	v_writelane_b32 v254, s1, 60
	s_and_b64 s[0:1], s[82:83], exec
	s_movk_i32 s0, 0x90
	s_cselect_b32 s13, s0, 0x80
	v_readlane_b32 s0, v254, 2
	v_readlane_b32 s1, v254, 3
	s_cselect_b32 s20, 0, 0x70
	v_writelane_b32 v254, s2, 61
	s_and_b64 s[0:1], s[0:1], s[2:3]
	s_and_b64 s[0:1], s[0:1], exec
	s_mul_i32 s21, s13, 11
	v_writelane_b32 v254, s3, 62
	s_cselect_b32 s0, 0xfffffdc0, 0
	s_cselect_b32 s51, 0x240, 0
	s_add_i32 s2, s21, s20
	s_add_i32 s0, s2, s0
	s_lshl_b32 s62, s16, 13
	s_lshl_b32 s36, s16, 3
	s_add_i32 s51, s51, s73
	s_cmp_lt_i32 s51, 2.0
	s_cselect_b64 s[4:5], -1, 0
	s_cmp_ge_i32 s51, s21
	s_cselect_b64 s[2:3], -1, 0
	v_writelane_b32 v254, s2, 63
	s_mov_b32 s15, s37
	s_mul_i32 s12, s16, 0x1800000
	v_writelane_b32 v255, s3, 0
	s_sub_i32 s2, s51, s21
	s_cmp_lt_i32 s2, s20
	s_cselect_b64 s[6:7], -1, 0
	s_ashr_i32 s3, s2, 4
	v_writelane_b32 v255, s6, 1
	s_cmp_gt_i32 s3, 2
	s_mul_i32 s1, s16, 0x2ec00
	v_writelane_b32 v255, s7, 2
	s_cselect_b32 s6, 4, 2
	s_add_i32 s6, s6, s3
	s_cmp_gt_u32 s2, 15
	s_cselect_b32 s2, s6, 0
	v_writelane_b32 v255, s2, 3
	s_ashr_i32 s2, s51, 31
	s_lshr_b32 s2, s2, 29
	s_add_i32 s2, s51, s2
	s_ashr_i32 s9, s2, 3
	s_and_b32 s6, s2, -8
	s_load_dwordx2 s[2:3], s[22:23], 0xf0
	s_lshr_b32 s18, s21, 3
	s_sub_i32 s10, s51, s6
	s_mov_b32 s6, s14
	v_writelane_b32 v255, s6, 4
	s_waitcnt lgkmcnt(0)
	s_add_u32 s19, s2, 0x5400000
	s_addc_u32 s42, s3, 0
	s_lshl_b64 s[14:15], s[14:15], 2
	v_writelane_b32 v255, s7, 5
	s_add_u32 s6, s2, s14
	v_writelane_b32 v255, s14, 6
	s_addc_u32 s7, s3, s15
	s_add_u32 s24, s6, 0x800000
	s_addc_u32 s25, s7, 0
	s_add_u32 s6, s2, s12
	s_addc_u32 s7, s3, 0
	s_add_u32 s43, s6, 0x1400000
	s_addc_u32 s46, s7, 0
	s_add_u32 s26, s2, 0x9c00000
	s_addc_u32 s27, s3, 0
	s_add_u32 s1, s2, s1
	s_addc_u32 s6, s3, 0
	s_add_u32 s47, s1, 0x200000
	s_addc_u32 s90, s6, 0
	s_add_u32 s28, s2, 0x400000
	s_addc_u32 s29, s3, 0
	v_mbcnt_lo_u32_b32 v200, -1, 0
	v_mbcnt_hi_u32_b32 v200, -1, v200
	v_lshl_add_u32 v200, s96, 6, v200
	v_lshlrev_b32_e32 v200, 4, v200
	global_load_dwordx4 v[202:205], v200, s[28:29]
	v_add_u32_e32 v200, 0x24000, v200
	s_ashr_i32 s1, s0, 31
	s_abs_i32 s0, s0
	v_readlane_b32 s6, v254, 29
	s_mul_hi_u32 s6, s0, s6
	v_readlane_b32 s7, v254, 30
	s_mul_i32 s6, s6, s7
	s_sub_i32 s0, s0, s6
	s_sub_i32 s6, s0, s7
	s_cmp_ge_u32 s0, s7
	s_cselect_b32 s0, s6, s0
	s_sub_i32 s6, s0, s7
	s_cmp_ge_u32 s0, s7
	s_cselect_b32 s0, s6, s0
	v_writelane_b32 v255, s15, 7
	s_xor_b32 s0, s0, s1
	v_writelane_b32 v255, s12, 8
	s_sub_i32 s12, s0, s1
	s_cmp_lg_u32 s12, 0
	s_cselect_b64 s[0:1], -1, 0
	s_mov_b32 s6, s12
	s_cmp_le_i32 s6, s85
	s_cselect_b64 s[6:7], -1, 0
	s_and_b64 s[30:31], s[0:1], s[6:7]
	s_cmp_lt_i32 s73, s12
	s_cselect_b64 s[38:39], -1, 0
	s_add_u32 s40, s2, 0x410000
	s_addc_u32 s41, s3, 0
	s_add_u32 s0, s2, 0x500000
	s_addc_u32 s1, s3, 0
	v_writelane_b32 v255, s0, 9
	s_sub_i32 s6, s73, s12
	s_mov_b32 s11, s96
	v_writelane_b32 v255, s1, 10
	s_and_b64 s[0:1], s[30:31], exec
	s_cselect_b32 s0, s6, s91
	s_lshl_b32 s91, s0, 3
	s_sub_i32 s0, s85, s12
	v_mbcnt_lo_u32_b32 v206, -1, 0
	v_mbcnt_hi_u32_b32 v206, -1, v206
	s_add_i32 s91, s91, s11
	s_lshl_b32 s6, s0, 3
	s_and_b64 s[0:1], s[30:31], exec
	v_readlane_b32 s0, v254, 49
	s_cselect_b32 s93, s6, s0
	s_cmp_lt_i32 s91, 0x9000
	s_cselect_b64 s[60:61], -1, 0
	s_sub_i32 s0, s93, s91
	s_mul_i32 s8, s16, 0x220
	v_readlane_b32 s1, v254, 50
	s_add_i32 s0, s0, 0x8fff
	s_add_u32 s1, s2, s8
	s_addc_u32 s6, s3, 0
	s_mov_b32 s14, s16
	s_add_u32 s16, s1, 0x280000
	s_addc_u32 s17, s6, 0
	v_readlane_b32 s6, v254, 40
	v_writelane_b32 v255, s16, 11
	v_readlane_b32 s7, v254, 41
	s_lshr_b32 s1, s10, 31
	v_writelane_b32 v255, s17, 12
	s_and_b64 s[16:17], s[6:7], s[4:5]
	s_abs_i32 s4, s93
	v_cvt_f32_u32_e32 v0, s4
	s_or_b32 s1, s18, s1
	s_mul_i32 s1, s1, s10
	s_add_i32 s1, s1, s9
	v_rcp_iflag_f32_e32 v0, v0
	s_mul_hi_i32 s5, s1, 0x2e8ba2e9
	s_lshr_b32 s6, s5, 31
	s_ashr_i32 s5, s5, 4
	v_mul_f32_e32 v0, 0x4f7ffffe, v0
	v_cvt_u32_f32_e32 v0, v0
	s_sub_i32 s7, 0, s4
	s_add_i32 s5, s5, s6
	s_lshl_b32 s6, s5, 3
	v_readfirstlane_b32 s8, v0
	s_mul_i32 s7, s7, s8
	s_mulk_i32 s5, 0x58
	s_mul_hi_u32 s7, s8, s7
	s_sub_i32 s1, s1, s5
	s_abs_i32 s5, s0
	s_add_i32 s8, s8, s7
	s_mul_hi_u32 s7, s5, s8
	s_mul_i32 s8, s7, s4
	s_sub_i32 s5, s5, s8
	s_sub_i32 s8, s13, s6
	s_xor_b32 s0, s0, s93
	s_min_i32 s8, s8, 8
	s_ashr_i32 s0, s0, 31
	s_add_i32 s9, s7, 1
	s_sub_i32 s10, s5, s4
	s_cmp_ge_u32 s5, s4
	s_cselect_b32 s7, s9, s7
	s_cselect_b32 s5, s10, s5
	s_add_i32 s9, s7, 1
	s_cmp_ge_u32 s5, s4
	s_cselect_b32 s4, s9, s7
	s_abs_i32 s5, s8
	v_cvt_f32_u32_e32 v0, s5
	s_xor_b32 s4, s4, s0
	v_writelane_b32 v255, s13, 13
	s_sub_i32 s0, s4, s0
	v_rcp_iflag_f32_e32 v0, v0
	v_writelane_b32 v255, s0, 14
	s_sub_i32 s0, 0, s5
	s_mov_b32 s15, s37
	v_mul_f32_e32 v0, 0x4f7ffffe, v0
	v_cvt_u32_f32_e32 v0, v0
	v_lshl_add_u32 v207, s11, 6, v206
	s_mov_b32 s50, s62
	v_readfirstlane_b32 s4, v0
	s_mul_i32 s0, s0, s4
	s_mul_hi_u32 s0, s4, s0
	s_add_i32 s4, s4, s0
	s_abs_i32 s0, s1
	s_mul_hi_u32 s4, s0, s4
	s_mul_i32 s7, s4, s5
	s_sub_i32 s0, s0, s7
	s_xor_b32 s7, s1, s8
	s_ashr_i32 s7, s7, 31
	s_add_i32 s9, s4, 1
	s_sub_i32 s10, s0, s5
	s_cmp_ge_u32 s0, s5
	s_cselect_b32 s4, s9, s4
	s_cselect_b32 s0, s10, s0
	s_add_i32 s9, s4, 1
	s_cmp_ge_u32 s0, s5
	s_cselect_b32 s0, s9, s4
	s_xor_b32 s0, s0, s7
	s_sub_i32 s0, s0, s7
	s_mov_b32 s89, s0
	s_mul_i32 s0, s0, s8
	s_sub_i32 s0, s1, s0
	s_add_i32 s0, s6, s0
	v_writelane_b32 v255, s0, 15
	v_writelane_b32 v255, s14, 16
	s_lshl_b64 s[0:1], s[14:15], 15
	s_add_u32 s0, s40, s0
	v_writelane_b32 v255, s15, 17
	s_addc_u32 s1, s41, s1
	v_writelane_b32 v255, s0, 18
	s_mov_b64 s[6:7], -1
	s_nop 0
	v_writelane_b32 v255, s1, 19
	s_add_u32 s0, s2, 0x5400070
	s_addc_u32 s1, s3, 0
	v_writelane_b32 v255, s0, 20
	s_nop 1
	v_writelane_b32 v255, s1, 21
	v_writelane_b32 v255, s16, 22
	s_nop 1
	v_writelane_b32 v255, s17, 23
	s_waitcnt vmcnt(0)
	ds_write_b128 v200, v[202:205]
	s_waitcnt lgkmcnt(0)
	s_branch .LBB0_334

.LBB0_479:
	s_andn2_b64 vcc, exec, s[14:15]
	s_cmp_lg_u32 s9, 0
	s_cselect_b64 s[52:53], -1, 0
	s_lshl_b64 s[10:11], s[10:11], 2
	s_add_u32 s10, s47, s10
	s_addc_u32 s11, s90, s11
	s_lshl_b32 s16, s8, 8
	s_add_i32 s16, s16, s88
	v_or_b32_e32 v200, s16, v208
	v_ashrrev_i32_e32 v201, 31, v200
	v_lshlrev_b64 v[4:5], 6, v[200:201]
	v_lshl_add_u64 v[24:25], v[184:185], 0, v[4:5]
	global_load_dwordx4 v[4:7], v[24:25], off
	v_or_b32_e32 v198, 16, v200
	v_ashrrev_i32_e32 v199, 31, v198
	v_lshlrev_b64 v[8:9], 6, v[198:199]
	v_lshl_add_u64 v[8:9], v[184:185], 0, v[8:9]
	global_load_dwordx4 v[8:11], v[8:9], off
	v_or_b32_e32 v196, 32, v200
	v_ashrrev_i32_e32 v197, 31, v196
	v_lshlrev_b64 v[12:13], 6, v[196:197]
	v_lshl_add_u64 v[12:13], v[184:185], 0, v[12:13]
	global_load_dwordx4 v[12:15], v[12:13], off
	v_or_b32_e32 v194, 48, v200
	v_ashrrev_i32_e32 v195, 31, v194
	v_lshlrev_b64 v[16:17], 6, v[194:195]
	v_lshl_add_u64 v[16:17], v[184:185], 0, v[16:17]
	global_load_dwordx4 v[16:19], v[16:17], off
	v_add_u32_e32 v192, 0x80, v200
	v_ashrrev_i32_e32 v193, 31, v192
	v_lshlrev_b64 v[20:21], 6, v[192:193]
	v_lshl_add_u64 v[20:21], v[184:185], 0, v[20:21]
	global_load_dwordx4 v[20:23], v[20:21], off
	v_add_co_u32_e32 v32, vcc, s59, v24
	v_lshl_add_u32 v190, s12, 8, v210
	s_nop 0
	v_addc_co_u32_e32 v33, vcc, 0, v25, vcc
	global_load_dwordx4 v[24:27], v[32:33], off offset:1024
	global_load_dwordx4 v[28:31], v[32:33], off offset:2048
	global_load_dwordx4 v[66:69], v[32:33], off offset:3072
	v_ashrrev_i32_e32 v191, 31, v190
	v_lshl_add_u64 v[2:3], v[190:191], 2, s[10:11]
	s_and_b64 s[10:11], s[6:7], s[52:53]
	s_andn2_b64 vcc, exec, s[10:11]
	s_waitcnt vmcnt(0)
	v_add_f32_e32 v4, v4, v5
	v_add_f32_e32 v5, v6, v7
	v_add_f32_e32 v4, v4, v5
	ds_swizzle_b32 v5, v4 offset:swizzle(SWAP,16)
	s_waitcnt lgkmcnt(0)
	v_add_f32_e32 v197, v4, v5
	v_add_f32_e32 v4, v8, v9
	v_add_f32_e32 v5, v10, v11
	v_add_f32_e32 v4, v4, v5
	ds_swizzle_b32 v5, v4 offset:swizzle(SWAP,16)
	v_mov_b32_e32 v202, v197
	s_nop 1
	v_permlane32_swap_b32_e32 v197, v202
	s_waitcnt lgkmcnt(0)
	v_add_f32_e32 v224, v4, v5
	v_add_f32_e32 v4, v12, v13
	v_add_f32_e32 v5, v14, v15
	v_add_f32_e32 v4, v4, v5
	ds_swizzle_b32 v5, v4 offset:swizzle(SWAP,16)
	v_mov_b32_e32 v225, v224
	s_nop 1
	v_permlane32_swap_b32_e32 v224, v225
	s_waitcnt lgkmcnt(0)
	v_add_f32_e32 v222, v4, v5
	v_add_f32_e32 v4, v16, v17
	v_add_f32_e32 v5, v18, v19
	v_add_f32_e32 v4, v4, v5
	ds_swizzle_b32 v5, v4 offset:swizzle(SWAP,16)
	v_mov_b32_e32 v223, v222
	s_nop 1
	v_permlane32_swap_b32_e32 v222, v223
	s_waitcnt lgkmcnt(0)
	v_add_f32_e32 v220, v4, v5
	v_add_f32_e32 v4, v20, v21
	v_add_f32_e32 v5, v22, v23
	v_add_f32_e32 v4, v4, v5
	ds_swizzle_b32 v5, v4 offset:swizzle(SWAP,16)
	v_mov_b32_e32 v221, v220
	s_nop 1
	v_permlane32_swap_b32_e32 v220, v221
	s_waitcnt lgkmcnt(0)
	v_add_f32_e32 v218, v4, v5
	v_add_f32_e32 v4, v24, v25
	v_add_f32_e32 v5, v26, v27
	v_add_f32_e32 v4, v4, v5
	ds_swizzle_b32 v5, v4 offset:swizzle(SWAP,16)
	v_mov_b32_e32 v219, v218
	s_nop 1
	v_permlane32_swap_b32_e32 v218, v219
	s_waitcnt lgkmcnt(0)
	v_add_f32_e32 v216, v4, v5
	v_add_f32_e32 v4, v28, v29
	v_add_f32_e32 v5, v30, v31
	v_add_f32_e32 v4, v4, v5
	ds_swizzle_b32 v5, v4 offset:swizzle(SWAP,16)
	v_mov_b32_e32 v217, v216
	s_nop 1
	v_permlane32_swap_b32_e32 v216, v217
	s_waitcnt lgkmcnt(0)
	v_add_f32_e32 v199, v4, v5
	v_add_f32_e32 v4, v66, v67
	v_add_f32_e32 v5, v68, v69
	global_load_dwordx4 v[82:85], v[2:3], off offset:16
	global_load_dwordx4 v[86:89], v[2:3], off
	global_load_dwordx4 v[66:69], v[2:3], off offset:528
	global_load_dwordx4 v[70:73], v[2:3], off offset:512
	v_add_f32_e32 v4, v4, v5
	ds_swizzle_b32 v5, v4 offset:swizzle(SWAP,16)
	v_mov_b32_e32 v201, v199
	v_cndmask_b32_e64 v2, 0, 1, s[10:11]
	s_nop 0
	v_permlane32_swap_b32_e32 v199, v201
	s_waitcnt lgkmcnt(0)
	v_add_f32_e32 v193, v4, v5
	v_mov_b32_e32 v195, v193
	s_nop 1
	v_permlane32_swap_b32_e32 v193, v195
	v_cmp_ne_u32_e64 s[14:15], 1, v2
	s_cbranch_vccnz .LBB0_481
	s_bfe_u32 s8, s16, 0x50006
	v_mov_b32_e32 v2, s8
	v_cndmask_b32_e64 v2, v208, v2, s[2:3]
	v_lshlrev_b32_e32 v3, 2, v211
	v_lshl_or_b32 v2, v2, 7, v3
	v_add_u32_e32 v2, 0x24000, v2
	ds_read_b128 v[14:17], v2 offset:48
	ds_read_b128 v[10:13], v2 offset:32
	ds_read_b128 v[6:9], v2 offset:16
	s_nop 0
	ds_read_b128 v[2:5], v2
.LBB0_481:
	s_and_b64 vcc, exec, s[14:15]
	v_mov_b32_e32 v18, 0
	s_cbranch_vccnz .LBB0_483
	s_bfe_u32 s8, s16, 0x50006
	v_mov_b32_e32 v18, s8
	v_cndmask_b32_e64 v18, v212, v18, s[2:3]
	v_lshlrev_b32_e32 v19, 2, v211
	v_lshl_or_b32 v18, v18, 7, v19
	v_add_u32_e32 v18, 0x24000, v18
	ds_read_b128 v[226:229], v18
	ds_read_b128 v[230:233], v18 offset:16
	ds_read_b128 v[234:237], v18 offset:32
	ds_read_b128 v[238:241], v18 offset:48
	s_waitcnt lgkmcnt(4)
	v_mov_b32_e32 v18, v2
	v_mov_b32_e32 v19, v3
	v_mov_b32_e32 v20, v4
	v_mov_b32_e32 v21, v5
	v_mov_b32_e32 v22, v6
	v_mov_b32_e32 v23, v7
	v_mov_b32_e32 v24, v8
	v_mov_b32_e32 v25, v9
	v_mov_b32_e32 v26, v10
	v_mov_b32_e32 v27, v11
	v_mov_b32_e32 v28, v12
	v_mov_b32_e32 v29, v13
	v_mov_b32_e32 v30, v14
	v_mov_b32_e32 v31, v15
	v_mov_b32_e32 v32, v16
	v_mov_b32_e32 v33, v17
	s_waitcnt lgkmcnt(3)
	v_mov_b64_e32 v[2:3], v[226:227]
	s_waitcnt lgkmcnt(2)
	v_mov_b64_e32 v[6:7], v[230:231]
	s_waitcnt lgkmcnt(1)
	v_mov_b64_e32 v[10:11], v[234:235]
	s_waitcnt lgkmcnt(0)
	v_mov_b64_e32 v[14:15], v[238:239]
	v_mov_b64_e32 v[4:5], v[228:229]
	v_mov_b64_e32 v[8:9], v[232:233]
	v_mov_b64_e32 v[12:13], v[236:237]
	v_mov_b64_e32 v[16:17], v[240:241]
	s_branch .LBB0_484

.LBB0_492:
	v_cvt_pk_bf16_f32 v166, v166, v167
	v_cvt_pk_bf16_f32 v167, v168, v169
	v_cvt_pk_bf16_f32 v168, v162, v163
	s_nop 0
	v_cvt_pk_bf16_f32 v169, v164, v165
	global_store_dwordx4 v[170:171], v[166:169], off offset:256
	s_and_b64 vcc, exec, s[14:15]
	s_cbranch_vccnz .LBB0_494
	s_bfe_u32 s17, s16, 0x50006
	v_mov_b32_e32 v18, s17
	v_cndmask_b32_e64 v18, v213, v18, s[2:3]
	v_lshlrev_b32_e32 v19, 2, v211
	v_lshl_or_b32 v18, v18, 7, v19
	v_add_u32_e32 v18, 0x24000, v18
	ds_read_b128 v[162:165], v18
	ds_read_b128 v[226:229], v18 offset:16
	ds_read_b128 v[230:233], v18 offset:32
	ds_read_b128 v[234:237], v18 offset:48
	v_mov_b64_e32 v[32:33], v[16:17]
	v_mov_b32_e32 v166, v2
	v_mov_b32_e32 v169, v3
	v_mov_b32_e32 v167, v4
	v_mov_b32_e32 v171, v5
	v_mov_b32_e32 v168, v6
	v_mov_b32_e32 v173, v7
	v_mov_b32_e32 v170, v8
	v_mov_b32_e32 v175, v9
	v_mov_b32_e32 v172, v10
	v_mov_b32_e32 v177, v11
	v_mov_b32_e32 v174, v12
	v_mov_b32_e32 v202, v13
	v_mov_b32_e32 v176, v14
	v_mov_b32_e32 v203, v15
	v_mov_b32_e32 v200, v16
	v_mov_b32_e32 v204, v17
	v_mov_b64_e32 v[30:31], v[14:15]
	v_mov_b64_e32 v[28:29], v[12:13]
	v_mov_b64_e32 v[26:27], v[10:11]
	v_mov_b64_e32 v[24:25], v[8:9]
	v_mov_b64_e32 v[22:23], v[6:7]
	v_mov_b64_e32 v[20:21], v[4:5]
	v_mov_b64_e32 v[18:19], v[2:3]
	s_waitcnt lgkmcnt(3)
	v_mov_b64_e32 v[2:3], v[162:163]
	s_waitcnt lgkmcnt(2)
	v_mov_b64_e32 v[6:7], v[226:227]
	s_waitcnt lgkmcnt(1)
	v_mov_b64_e32 v[10:11], v[230:231]
	s_waitcnt lgkmcnt(0)
	v_mov_b64_e32 v[14:15], v[234:235]
	v_mov_b64_e32 v[4:5], v[164:165]
	v_mov_b64_e32 v[8:9], v[228:229]
	v_mov_b64_e32 v[12:13], v[232:233]
	v_mov_b64_e32 v[16:17], v[236:237]
	s_branch .LBB0_495

.LBB0_503:
	v_cvt_pk_bf16_f32 v150, v150, v151
	v_cvt_pk_bf16_f32 v151, v152, v153
	v_cvt_pk_bf16_f32 v152, v146, v147
	s_nop 0
	v_cvt_pk_bf16_f32 v153, v148, v149
	global_store_dwordx4 v[154:155], v[150:153], off offset:256
	s_and_b64 vcc, exec, s[14:15]
	s_cbranch_vccnz .LBB0_505
	s_bfe_u32 s16, s16, 0x50006
	v_mov_b32_e32 v18, s16
	v_cndmask_b32_e64 v18, v214, v18, s[2:3]
	v_lshlrev_b32_e32 v19, 2, v211
	v_lshl_or_b32 v18, v18, 7, v19
	v_add_u32_e32 v18, 0x24000, v18
	ds_read_b128 v[146:149], v18
	ds_read_b128 v[150:153], v18 offset:16
	ds_read_b128 v[154:157], v18 offset:32
	ds_read_b128 v[158:161], v18 offset:48
	v_mov_b64_e32 v[32:33], v[16:17]
	v_mov_b32_e32 v166, v2
	v_mov_b32_e32 v169, v3
	v_mov_b32_e32 v167, v4
	v_mov_b32_e32 v171, v5
	v_mov_b32_e32 v168, v6
	v_mov_b32_e32 v173, v7
	v_mov_b32_e32 v170, v8
	v_mov_b32_e32 v175, v9
	v_mov_b32_e32 v172, v10
	v_mov_b32_e32 v177, v11
	v_mov_b32_e32 v174, v12
	v_mov_b32_e32 v202, v13
	v_mov_b32_e32 v176, v14
	v_mov_b32_e32 v203, v15
	v_mov_b32_e32 v200, v16
	v_mov_b32_e32 v204, v17
	v_mov_b64_e32 v[30:31], v[14:15]
	v_mov_b64_e32 v[28:29], v[12:13]
	v_mov_b64_e32 v[26:27], v[10:11]
	v_mov_b64_e32 v[24:25], v[8:9]
	v_mov_b64_e32 v[22:23], v[6:7]
	v_mov_b64_e32 v[20:21], v[4:5]
	v_mov_b64_e32 v[18:19], v[2:3]
	s_waitcnt lgkmcnt(3)
	v_mov_b64_e32 v[2:3], v[146:147]
	s_waitcnt lgkmcnt(2)
	v_mov_b64_e32 v[6:7], v[150:151]
	s_waitcnt lgkmcnt(1)
	v_mov_b64_e32 v[10:11], v[154:155]
	s_waitcnt lgkmcnt(0)
	v_mov_b64_e32 v[14:15], v[158:159]
	v_mov_b64_e32 v[4:5], v[148:149]
	v_mov_b64_e32 v[8:9], v[152:153]
	v_mov_b64_e32 v[12:13], v[156:157]
	v_mov_b64_e32 v[16:17], v[160:161]

.LBB0_513:
	v_cvt_pk_bf16_f32 v134, v134, v135
	v_cvt_pk_bf16_f32 v135, v136, v137
	v_cvt_pk_bf16_f32 v136, v130, v131
	s_nop 0
	v_cvt_pk_bf16_f32 v137, v132, v133
	global_store_dwordx4 v[138:139], v[134:137], off offset:256
	s_and_b64 vcc, exec, s[14:15]
	s_cbranch_vccnz .LBB0_515
	v_bfe_u32 v18, v192, 6, 5
	v_cndmask_b32_e64 v18, v208, v18, s[2:3]
	v_lshlrev_b32_e32 v19, 2, v211
	v_lshl_or_b32 v18, v18, 7, v19
	v_add_u32_e32 v18, 0x24000, v18
	ds_read_b128 v[130:133], v18
	ds_read_b128 v[134:137], v18 offset:16
	ds_read_b128 v[138:141], v18 offset:32
	ds_read_b128 v[142:145], v18 offset:48
	v_mov_b64_e32 v[32:33], v[16:17]
	v_mov_b32_e32 v166, v2
	v_mov_b32_e32 v169, v3
	v_mov_b32_e32 v167, v4
	v_mov_b32_e32 v171, v5
	v_mov_b32_e32 v168, v6
	v_mov_b32_e32 v173, v7
	v_mov_b32_e32 v170, v8
	v_mov_b32_e32 v175, v9
	v_mov_b32_e32 v172, v10
	v_mov_b32_e32 v177, v11
	v_mov_b32_e32 v174, v12
	v_mov_b32_e32 v202, v13
	v_mov_b32_e32 v176, v14
	v_mov_b32_e32 v203, v15
	v_mov_b32_e32 v200, v16
	v_mov_b32_e32 v204, v17
	v_mov_b64_e32 v[30:31], v[14:15]
	v_mov_b64_e32 v[28:29], v[12:13]
	v_mov_b64_e32 v[26:27], v[10:11]
	v_mov_b64_e32 v[24:25], v[8:9]
	v_mov_b64_e32 v[22:23], v[6:7]
	v_mov_b64_e32 v[20:21], v[4:5]
	v_mov_b64_e32 v[18:19], v[2:3]
	s_waitcnt lgkmcnt(3)
	v_mov_b64_e32 v[2:3], v[130:131]
	s_waitcnt lgkmcnt(2)
	v_mov_b64_e32 v[6:7], v[134:135]
	s_waitcnt lgkmcnt(1)
	v_mov_b64_e32 v[10:11], v[138:139]
	s_waitcnt lgkmcnt(0)
	v_mov_b64_e32 v[14:15], v[142:143]
	v_mov_b64_e32 v[4:5], v[132:133]
	v_mov_b64_e32 v[8:9], v[136:137]
	v_mov_b64_e32 v[12:13], v[140:141]
	v_mov_b64_e32 v[16:17], v[144:145]

.LBB0_523:
	v_cvt_pk_bf16_f32 v118, v118, v119
	v_cvt_pk_bf16_f32 v119, v120, v121
	v_cvt_pk_bf16_f32 v120, v114, v115
	s_nop 0
	v_cvt_pk_bf16_f32 v121, v116, v117
	global_store_dwordx4 v[122:123], v[118:121], off offset:256
	s_and_b64 vcc, exec, s[14:15]
	s_cbranch_vccnz .LBB0_525
	v_bfe_u32 v18, v192, 6, 5
	v_cndmask_b32_e64 v18, v212, v18, s[2:3]
	v_lshlrev_b32_e32 v19, 2, v211
	v_lshl_or_b32 v18, v18, 7, v19
	v_add_u32_e32 v18, 0x24000, v18
	ds_read_b128 v[114:117], v18
	ds_read_b128 v[118:121], v18 offset:16
	ds_read_b128 v[122:125], v18 offset:32
	ds_read_b128 v[126:129], v18 offset:48
	v_mov_b64_e32 v[32:33], v[16:17]
	v_mov_b32_e32 v166, v2
	v_mov_b32_e32 v169, v3
	v_mov_b32_e32 v167, v4
	v_mov_b32_e32 v171, v5
	v_mov_b32_e32 v168, v6
	v_mov_b32_e32 v173, v7
	v_mov_b32_e32 v170, v8
	v_mov_b32_e32 v175, v9
	v_mov_b32_e32 v172, v10
	v_mov_b32_e32 v177, v11
	v_mov_b32_e32 v174, v12
	v_mov_b32_e32 v202, v13
	v_mov_b32_e32 v176, v14
	v_mov_b32_e32 v203, v15
	v_mov_b32_e32 v200, v16
	v_mov_b32_e32 v204, v17
	v_mov_b64_e32 v[30:31], v[14:15]
	v_mov_b64_e32 v[28:29], v[12:13]
	v_mov_b64_e32 v[26:27], v[10:11]
	v_mov_b64_e32 v[24:25], v[8:9]
	v_mov_b64_e32 v[22:23], v[6:7]
	v_mov_b64_e32 v[20:21], v[4:5]
	v_mov_b64_e32 v[18:19], v[2:3]
	s_waitcnt lgkmcnt(3)
	v_mov_b64_e32 v[2:3], v[114:115]
	s_waitcnt lgkmcnt(2)
	v_mov_b64_e32 v[6:7], v[118:119]
	s_waitcnt lgkmcnt(1)
	v_mov_b64_e32 v[10:11], v[122:123]
	s_waitcnt lgkmcnt(0)
	v_mov_b64_e32 v[14:15], v[126:127]
	v_mov_b64_e32 v[4:5], v[116:117]
	v_mov_b64_e32 v[8:9], v[120:121]
	v_mov_b64_e32 v[12:13], v[124:125]
	v_mov_b64_e32 v[16:17], v[128:129]

.LBB0_533:
	v_cvt_pk_bf16_f32 v102, v102, v103
	v_cvt_pk_bf16_f32 v103, v104, v105
	v_cvt_pk_bf16_f32 v104, v98, v99
	s_nop 0
	v_cvt_pk_bf16_f32 v105, v100, v101
	global_store_dwordx4 v[106:107], v[102:105], off offset:256
	s_and_b64 vcc, exec, s[14:15]
	s_cbranch_vccnz .LBB0_535
	v_bfe_u32 v18, v192, 6, 5
	v_cndmask_b32_e64 v18, v213, v18, s[2:3]
	v_lshlrev_b32_e32 v19, 2, v211
	v_lshl_or_b32 v18, v18, 7, v19
	v_add_u32_e32 v18, 0x24000, v18
	ds_read_b128 v[98:101], v18
	ds_read_b128 v[102:105], v18 offset:16
	ds_read_b128 v[106:109], v18 offset:32
	ds_read_b128 v[110:113], v18 offset:48
	v_mov_b64_e32 v[32:33], v[16:17]
	v_mov_b32_e32 v166, v2
	v_mov_b32_e32 v169, v3
	v_mov_b32_e32 v167, v4
	v_mov_b32_e32 v171, v5
	v_mov_b32_e32 v168, v6
	v_mov_b32_e32 v173, v7
	v_mov_b32_e32 v170, v8
	v_mov_b32_e32 v175, v9
	v_mov_b32_e32 v172, v10
	v_mov_b32_e32 v177, v11
	v_mov_b32_e32 v174, v12
	v_mov_b32_e32 v202, v13
	v_mov_b32_e32 v176, v14
	v_mov_b32_e32 v203, v15
	v_mov_b32_e32 v200, v16
	v_mov_b32_e32 v204, v17
	v_mov_b64_e32 v[30:31], v[14:15]
	v_mov_b64_e32 v[28:29], v[12:13]
	v_mov_b64_e32 v[26:27], v[10:11]
	v_mov_b64_e32 v[24:25], v[8:9]
	v_mov_b64_e32 v[22:23], v[6:7]
	v_mov_b64_e32 v[20:21], v[4:5]
	v_mov_b64_e32 v[18:19], v[2:3]
	s_waitcnt lgkmcnt(3)
	v_mov_b64_e32 v[2:3], v[98:99]
	s_waitcnt lgkmcnt(2)
	v_mov_b64_e32 v[6:7], v[102:103]
	s_waitcnt lgkmcnt(1)
	v_mov_b64_e32 v[10:11], v[106:107]
	s_waitcnt lgkmcnt(0)
	v_mov_b64_e32 v[14:15], v[110:111]
	v_mov_b64_e32 v[4:5], v[100:101]
	v_mov_b64_e32 v[8:9], v[104:105]
	v_mov_b64_e32 v[12:13], v[108:109]
	v_mov_b64_e32 v[16:17], v[112:113]

.LBB0_543:
	v_cvt_pk_bf16_f32 v78, v78, v79
	v_cvt_pk_bf16_f32 v79, v80, v81
	v_cvt_pk_bf16_f32 v80, v74, v75
	s_nop 0
	v_cvt_pk_bf16_f32 v81, v76, v77
	global_store_dwordx4 v[90:91], v[78:81], off offset:256
	s_and_b64 vcc, exec, s[14:15]
	s_cbranch_vccnz .LBB0_545
	v_bfe_u32 v18, v192, 6, 5
	v_cndmask_b32_e64 v18, v214, v18, s[2:3]
	v_lshlrev_b32_e32 v19, 2, v211
	v_lshl_or_b32 v18, v18, 7, v19
	v_add_u32_e32 v18, 0x24000, v18
	ds_read_b128 v[74:77], v18
	ds_read_b128 v[78:81], v18 offset:16
	ds_read_b128 v[90:93], v18 offset:32
	ds_read_b128 v[94:97], v18 offset:48
	v_mov_b64_e32 v[32:33], v[16:17]
	v_mov_b32_e32 v166, v2
	v_mov_b32_e32 v169, v3
	v_mov_b32_e32 v167, v4
	v_mov_b32_e32 v171, v5
	v_mov_b32_e32 v168, v6
	v_mov_b32_e32 v173, v7
	v_mov_b32_e32 v170, v8
	v_mov_b32_e32 v175, v9
	v_mov_b32_e32 v172, v10
	v_mov_b32_e32 v177, v11
	v_mov_b32_e32 v174, v12
	v_mov_b32_e32 v202, v13
	v_mov_b32_e32 v176, v14
	v_mov_b32_e32 v203, v15
	v_mov_b32_e32 v200, v16
	v_mov_b32_e32 v204, v17
	v_mov_b64_e32 v[30:31], v[14:15]
	v_mov_b64_e32 v[28:29], v[12:13]
	v_mov_b64_e32 v[26:27], v[10:11]
	v_mov_b64_e32 v[24:25], v[8:9]
	v_mov_b64_e32 v[22:23], v[6:7]
	v_mov_b64_e32 v[20:21], v[4:5]
	v_mov_b64_e32 v[18:19], v[2:3]
	s_waitcnt lgkmcnt(3)
	v_mov_b64_e32 v[2:3], v[74:75]
	s_waitcnt lgkmcnt(2)
	v_mov_b64_e32 v[6:7], v[78:79]
	s_waitcnt lgkmcnt(1)
	v_mov_b64_e32 v[10:11], v[90:91]
	s_waitcnt lgkmcnt(0)
	v_mov_b64_e32 v[14:15], v[94:95]
	v_mov_b64_e32 v[4:5], v[76:77]
	v_mov_b64_e32 v[8:9], v[80:81]
	v_mov_b64_e32 v[12:13], v[92:93]
	v_mov_b64_e32 v[16:17], v[96:97]
